# GU/Down K-loops: first K-iteration peeled with srcC = 0 in the 32 MFMAs that first write each accumulator; the 128 v_mov accumulator zeroing per unit deleted
# baseline (speedup 1.0000x reference)
.LBB0_1679:
	s_add_u32 s21, s34, 0x100000
	s_addc_u32 s48, s35, 0
	s_add_u32 s30, s30, 0x40080
	s_addc_u32 s31, s31, 0
	s_mov_b32 s49, -2
	ds_read_b128 v[142:145], v138
	ds_read_b128 v[146:149], v138 offset:1024
	ds_read_b128 v[150:153], v138 offset:2048
	ds_read_b128 v[154:157], v138 offset:3072
	ds_read_b128 v[158:161], v139
	ds_read_b128 v[162:165], v139 offset:1024
	ds_read_b128 v[166:169], v139 offset:2048
	ds_read_b128 v[170:173], v139 offset:3072
	s_add_u32 s34, s30, 0xfffc0080
	s_addc_u32 s35, s31, -1
	s_cmp_eq_u32 s49, 12
	s_cselect_b32 s35, s23, s35
	s_cselect_b32 s34, s22, s34
	s_cselect_b32 s37, s25, s48
	s_cselect_b32 s36, s24, s21
	v_mov_b32_e32 v128, v133
	v_mov_b32_e32 v130, v134
	s_add_i32 m0, s41, 0xc000
	ds_read_b128 v[174:177], v140
	ds_read_b128 v[178:181], v140 offset:1024
	ds_read_b128 v[182:185], v140 offset:2048
	ds_read_b128 v[186:189], v140 offset:3072
	ds_read_b128 v[190:193], v140 offset:4096
	ds_read_b128 v[194:197], v140 offset:5120
	ds_read_b128 v[198:201], v140 offset:6144
	ds_read_b128 v[202:205], v140 offset:7168
	s_nop 0
	global_load_lds_dwordx4 v128, s[30:31]
	s_add_i32 m0, s41, 0xe000
	s_nop 0
	global_load_lds_dwordx4 v130, s[30:31]
	s_and_b64 vcc, exec, s[14:15]
	s_cbranch_vccnz .Lmy_p1lw_5
	s_waitcnt vmcnt(8)
.Lmy_p1lw_5:
	s_waitcnt lgkmcnt(0)
	s_barrier
	s_setprio 1
	s_waitcnt lgkmcnt(0)
	v_mfma_scale_f32_16x16x128_f8f6f4 v[124:127], v[142:149], v[174:181], 0, v141, v141 op_sel_hi:[0,0,0]
	v_mfma_scale_f32_16x16x128_f8f6f4 v[116:119], v[150:157], v[174:181], 0, v141, v141 op_sel_hi:[0,0,0]
	v_mfma_scale_f32_16x16x128_f8f6f4 v[108:111], v[142:149], v[182:189], 0, v141, v141 op_sel_hi:[0,0,0]
	v_mfma_scale_f32_16x16x128_f8f6f4 v[100:103], v[150:157], v[182:189], 0, v141, v141 op_sel_hi:[0,0,0]
	v_mfma_scale_f32_16x16x128_f8f6f4 v[206:209], v[142:149], v[190:197], 0, v141, v141 op_sel_hi:[0,0,0]
	v_mfma_scale_f32_16x16x128_f8f6f4 v[210:213], v[150:157], v[190:197], 0, v141, v141 op_sel_hi:[0,0,0]
	v_mfma_scale_f32_16x16x128_f8f6f4 v[214:217], v[142:149], v[198:205], 0, v141, v141 op_sel_hi:[0,0,0]
	v_mfma_scale_f32_16x16x128_f8f6f4 v[218:221], v[150:157], v[198:205], 0, v141, v141 op_sel_hi:[0,0,0]
	s_setprio 0
	s_setprio 1
	v_mfma_scale_f32_16x16x128_f8f6f4 v[120:123], v[158:165], v[174:181], 0, v141, v141 op_sel_hi:[0,0,0]
	v_mfma_scale_f32_16x16x128_f8f6f4 v[112:115], v[166:173], v[174:181], 0, v141, v141 op_sel_hi:[0,0,0]
	v_mfma_scale_f32_16x16x128_f8f6f4 v[104:107], v[158:165], v[182:189], 0, v141, v141 op_sel_hi:[0,0,0]
	v_mfma_scale_f32_16x16x128_f8f6f4 v[96:99], v[166:173], v[182:189], 0, v141, v141 op_sel_hi:[0,0,0]
	v_mfma_scale_f32_16x16x128_f8f6f4 v[174:177], v[158:165], v[190:197], 0, v141, v141 op_sel_hi:[0,0,0]
	v_mfma_scale_f32_16x16x128_f8f6f4 v[178:181], v[166:173], v[190:197], 0, v141, v141 op_sel_hi:[0,0,0]
	v_mfma_scale_f32_16x16x128_f8f6f4 v[182:185], v[158:165], v[198:205], 0, v141, v141 op_sel_hi:[0,0,0]
	v_mfma_scale_f32_16x16x128_f8f6f4 v[186:189], v[166:173], v[198:205], 0, v141, v141 op_sel_hi:[0,0,0]
	s_setprio 0
	s_waitcnt vmcnt(8)
	s_barrier
	s_add_i32 s64, s54, s3
	v_mov_b32_e32 v128, v135
	v_mov_b32_e32 v130, v136
	s_mov_b32 m0, s64
	s_nop 0
	ds_read_b128 v[64:67], v140 offset:16384
	ds_read_b128 v[68:71], v140 offset:17408
	ds_read_b128 v[72:75], v140 offset:18432
	ds_read_b128 v[76:79], v140 offset:19456
	ds_read_b128 v[80:83], v140 offset:20480
	ds_read_b128 v[84:87], v140 offset:21504
	ds_read_b128 v[88:91], v140 offset:22528
	ds_read_b128 v[92:95], v140 offset:23552
	v_mov_b32_e32 v131, v129
	global_load_lds_dwordx4 v128, s[36:37]
	s_add_i32 m0, s64, 0x2000
	v_mov_b32_e32 v128, v135
	global_load_lds_dwordx4 v130, s[36:37]
	v_mov_b32_e32 v130, v136
	s_add_i32 s64, s55, s3
	v_lshl_add_u64 v[190:191], s[36:37], 0, v[128:129]
	v_lshl_add_u64 v[190:191], v[190:191], 0, s[8:9]
	s_mov_b32 m0, s64
	v_lshl_add_u64 v[130:131], s[36:37], 0, v[130:131]
	global_load_lds_dwordx4 v[190:191], off
	v_lshl_add_u64 v[130:131], v[130:131], 0, s[8:9]
	s_add_i32 m0, s64, 0x2000
	v_mov_b32_e32 v128, v133
	global_load_lds_dwordx4 v[130:131], off
	v_mov_b32_e32 v130, v134
	s_mov_b32 m0, s41
	s_nop 0
	global_load_lds_dwordx4 v128, s[34:35]
	s_mov_b32 m0, s42
	s_nop 0
	global_load_lds_dwordx4 v130, s[34:35]
	s_and_b64 vcc, exec, s[14:15]
	s_cbranch_vccnz .Lmy_p1lw_6
	s_waitcnt vmcnt(8)
.Lmy_p1lw_6:
	s_waitcnt lgkmcnt(0)
	s_barrier
	s_setprio 1
	s_waitcnt lgkmcnt(0)
	v_mfma_scale_f32_16x16x128_f8f6f4 v[60:63], v[142:149], v[64:71], 0, v141, v141 op_sel_hi:[0,0,0]
	v_mfma_scale_f32_16x16x128_f8f6f4 v[52:55], v[150:157], v[64:71], 0, v141, v141 op_sel_hi:[0,0,0]
	v_mfma_scale_f32_16x16x128_f8f6f4 v[44:47], v[142:149], v[72:79], 0, v141, v141 op_sel_hi:[0,0,0]
	v_mfma_scale_f32_16x16x128_f8f6f4 v[198:201], v[150:157], v[72:79], 0, v141, v141 op_sel_hi:[0,0,0]
	v_mfma_scale_f32_16x16x128_f8f6f4 v[202:205], v[142:149], v[80:87], 0, v141, v141 op_sel_hi:[0,0,0]
	v_mfma_scale_f32_16x16x128_f8f6f4 v[222:225], v[150:157], v[80:87], 0, v141, v141 op_sel_hi:[0,0,0]
	v_mfma_scale_f32_16x16x128_f8f6f4 v[226:229], v[142:149], v[88:95], 0, v141, v141 op_sel_hi:[0,0,0]
	v_mfma_scale_f32_16x16x128_f8f6f4 v[230:233], v[150:157], v[88:95], 0, v141, v141 op_sel_hi:[0,0,0]
	s_setprio 0
	s_setprio 1
	v_mfma_scale_f32_16x16x128_f8f6f4 v[56:59], v[158:165], v[64:71], 0, v141, v141 op_sel_hi:[0,0,0]
	v_mfma_scale_f32_16x16x128_f8f6f4 v[48:51], v[166:173], v[64:71], 0, v141, v141 op_sel_hi:[0,0,0]
	v_mfma_scale_f32_16x16x128_f8f6f4 v[40:43], v[158:165], v[72:79], 0, v141, v141 op_sel_hi:[0,0,0]
	v_mfma_scale_f32_16x16x128_f8f6f4 v[234:237], v[166:173], v[72:79], 0, v141, v141 op_sel_hi:[0,0,0]
	v_mfma_scale_f32_16x16x128_f8f6f4 v[238:241], v[158:165], v[80:87], 0, v141, v141 op_sel_hi:[0,0,0]
	v_mfma_scale_f32_16x16x128_f8f6f4 v[242:245], v[166:173], v[80:87], 0, v141, v141 op_sel_hi:[0,0,0]
	v_mfma_scale_f32_16x16x128_f8f6f4 v[246:249], v[158:165], v[88:95], 0, v141, v141 op_sel_hi:[0,0,0]
	v_mfma_scale_f32_16x16x128_f8f6f4 v[250:253], v[166:173], v[88:95], 0, v141, v141 op_sel_hi:[0,0,0]
	s_setprio 0
	s_waitcnt vmcnt(8)
	s_barrier
	s_add_i32 s66, 0, 0x18000
	s_nop 2
	v_add_u32_e32 v8, s66, v137
	s_add_i32 s67, 0, 0x1c000
	ds_read_b128 v[0:3], v8
	ds_read_b128 v[4:7], v8 offset:1024
	ds_read_b128 v[142:145], v8 offset:2048
	ds_read_b128 v[146:149], v8 offset:3072
	v_add_u32_e32 v8, s67, v137
	ds_read_b128 v[150:153], v8
	ds_read_b128 v[154:157], v8 offset:1024
	ds_read_b128 v[158:161], v8 offset:2048
	ds_read_b128 v[162:165], v8 offset:3072
	s_add_u32 s64, s34, 0x40000
	v_mov_b32_e32 v64, v133
	v_mov_b32_e32 v65, v134
	s_addc_u32 s65, s35, 0
	s_mov_b32 m0, s43
	ds_read_b128 v[8:11], v140 offset:32768
	ds_read_b128 v[12:15], v140 offset:33792
	ds_read_b128 v[16:19], v140 offset:34816
	ds_read_b128 v[20:23], v140 offset:35840
	ds_read_b128 v[24:27], v140 offset:36864
	ds_read_b128 v[28:31], v140 offset:37888
	ds_read_b128 v[32:35], v140 offset:38912
	ds_read_b128 v[36:39], v140 offset:39936
	s_nop 0
	global_load_lds_dwordx4 v64, s[64:65]
	s_mov_b32 m0, s44
	s_nop 0
	global_load_lds_dwordx4 v65, s[64:65]
	s_and_b64 vcc, exec, s[14:15]
	s_cbranch_vccnz .Lmy_p1lw_7
	s_waitcnt vmcnt(8)

.Lmy_p1lw_8:
	s_waitcnt lgkmcnt(0)
	s_barrier
	s_setprio 1
	s_waitcnt lgkmcnt(0)
	v_mfma_scale_f32_16x16x128_f8f6f4 v[60:63], v[0:7], v[166:173], v[60:63], v141, v141 op_sel_hi:[0,0,0]
	v_mfma_scale_f32_16x16x128_f8f6f4 v[52:55], v[142:149], v[166:173], v[52:55], v141, v141 op_sel_hi:[0,0,0]
	v_mfma_scale_f32_16x16x128_f8f6f4 v[44:47], v[0:7], v[174:181], v[44:47], v141, v141 op_sel_hi:[0,0,0]
	v_mfma_scale_f32_16x16x128_f8f6f4 v[36:39], v[142:149], v[174:181], v[198:201], v141, v141 op_sel_hi:[0,0,0]
	v_mfma_scale_f32_16x16x128_f8f6f4 v[28:31], v[0:7], v[182:189], v[202:205], v141, v141 op_sel_hi:[0,0,0]
	v_mfma_scale_f32_16x16x128_f8f6f4 v[20:23], v[142:149], v[182:189], v[222:225], v141, v141 op_sel_hi:[0,0,0]
	v_mfma_scale_f32_16x16x128_f8f6f4 v[12:15], v[0:7], v[190:197], v[226:229], v141, v141 op_sel_hi:[0,0,0]
	v_mfma_scale_f32_16x16x128_f8f6f4 v[4:7], v[142:149], v[190:197], v[230:233], v141, v141 op_sel_hi:[0,0,0]
	s_setprio 0
	s_setprio 1
	v_mfma_scale_f32_16x16x128_f8f6f4 v[56:59], v[150:157], v[166:173], v[56:59], v141, v141 op_sel_hi:[0,0,0]
	v_mfma_scale_f32_16x16x128_f8f6f4 v[48:51], v[158:165], v[166:173], v[48:51], v141, v141 op_sel_hi:[0,0,0]
	v_mfma_scale_f32_16x16x128_f8f6f4 v[40:43], v[150:157], v[174:181], v[40:43], v141, v141 op_sel_hi:[0,0,0]
	v_mfma_scale_f32_16x16x128_f8f6f4 v[32:35], v[158:165], v[174:181], v[234:237], v141, v141 op_sel_hi:[0,0,0]
	v_mfma_scale_f32_16x16x128_f8f6f4 v[24:27], v[150:157], v[182:189], v[238:241], v141, v141 op_sel_hi:[0,0,0]
	v_mfma_scale_f32_16x16x128_f8f6f4 v[16:19], v[158:165], v[182:189], v[242:245], v141, v141 op_sel_hi:[0,0,0]
	v_mfma_scale_f32_16x16x128_f8f6f4 v[8:11], v[150:157], v[190:197], v[246:249], v141, v141 op_sel_hi:[0,0,0]
	v_mfma_scale_f32_16x16x128_f8f6f4 v[0:3], v[158:165], v[190:197], v[250:253], v141, v141 op_sel_hi:[0,0,0]
	s_setprio 0
	s_waitcnt vmcnt(8)
	s_barrier
	s_add_i32 s49, s49, 2
	s_add_u32 s21, s21, 0x100000
	s_addc_u32 s48, s48, 0
	s_add_u32 s30, s30, 0x100
	s_addc_u32 s31, s31, 0
	s_cmp_gt_u32 s49, 13
.LBB0_1680:
	ds_read_b128 v[142:145], v138
	ds_read_b128 v[146:149], v138 offset:1024
	ds_read_b128 v[150:153], v138 offset:2048
	ds_read_b128 v[154:157], v138 offset:3072
	ds_read_b128 v[158:161], v139
	ds_read_b128 v[162:165], v139 offset:1024
	ds_read_b128 v[166:169], v139 offset:2048
	ds_read_b128 v[170:173], v139 offset:3072
	s_add_u32 s34, s30, 0xfffc0080
	s_addc_u32 s35, s31, -1
	s_cmp_eq_u32 s49, 12
	s_cselect_b32 s35, s23, s35
	s_cselect_b32 s34, s22, s34
	s_cselect_b32 s37, s25, s48
	s_cselect_b32 s36, s24, s21
	v_mov_b32_e32 v128, v133
	v_mov_b32_e32 v130, v134
	s_add_i32 m0, s41, 0xc000
	ds_read_b128 v[174:177], v140
	ds_read_b128 v[178:181], v140 offset:1024
	ds_read_b128 v[182:185], v140 offset:2048
	ds_read_b128 v[186:189], v140 offset:3072
	ds_read_b128 v[190:193], v140 offset:4096
	ds_read_b128 v[194:197], v140 offset:5120
	ds_read_b128 v[198:201], v140 offset:6144
	ds_read_b128 v[202:205], v140 offset:7168
	s_nop 0
	global_load_lds_dwordx4 v128, s[30:31]
	s_add_i32 m0, s41, 0xe000
	s_nop 0
	global_load_lds_dwordx4 v130, s[30:31]
	s_and_b64 vcc, exec, s[14:15]
	s_cbranch_vccnz .Lmy_lw_5
	s_waitcnt vmcnt(8)

.LBB0_1750:
	s_add_u32 s19, s30, 0x80000
	s_addc_u32 s48, s31, 0
	s_add_u32 s28, s28, 0x40080
	s_addc_u32 s29, s29, 0
	s_mov_b32 s49, -2
	ds_read_b128 v[144:147], v140
	ds_read_b128 v[148:151], v140 offset:1024
	ds_read_b128 v[152:155], v140 offset:2048
	ds_read_b128 v[156:159], v140 offset:3072
	ds_read_b128 v[160:163], v141
	ds_read_b128 v[164:167], v141 offset:1024
	ds_read_b128 v[168:171], v141 offset:2048
	ds_read_b128 v[172:175], v141 offset:3072
	s_add_u32 s30, s28, 0xfffc0080
	s_addc_u32 s31, s29, -1
	s_cmp_eq_u32 s49, 12
	s_cselect_b32 s31, s21, s31
	s_cselect_b32 s30, s20, s30
	s_cselect_b32 s35, s23, s48
	s_cselect_b32 s34, s22, s19
	v_mov_b32_e32 v128, v136
	v_mov_b32_e32 v130, v135
	s_add_i32 m0, s40, 0xc000
	ds_read_b128 v[176:179], v142
	ds_read_b128 v[180:183], v142 offset:1024
	ds_read_b128 v[184:187], v142 offset:2048
	ds_read_b128 v[188:191], v142 offset:3072
	ds_read_b128 v[192:195], v142 offset:4096
	ds_read_b128 v[196:199], v142 offset:5120
	ds_read_b128 v[200:203], v142 offset:6144
	ds_read_b128 v[204:207], v142 offset:7168
	s_nop 0
	global_load_lds_dwordx4 v130, s[28:29]
	s_add_i32 m0, s40, 0xe000
	s_nop 0
	global_load_lds_dwordx4 v128, s[28:29]
	s_and_b64 vcc, exec, s[14:15]
	s_cbranch_vccnz .Lmy_p2lw_9
	s_waitcnt vmcnt(8)
.Lmy_p2lw_9:
	s_waitcnt lgkmcnt(0)
	s_barrier
	s_setprio 1
	s_waitcnt lgkmcnt(0)
	v_mfma_scale_f32_16x16x128_f8f6f4 v[124:127], v[144:151], v[176:183], 0, v143, v143 op_sel_hi:[0,0,0]
	v_mfma_scale_f32_16x16x128_f8f6f4 v[120:123], v[152:159], v[176:183], 0, v143, v143 op_sel_hi:[0,0,0]
	v_mfma_scale_f32_16x16x128_f8f6f4 v[112:115], v[144:151], v[184:191], 0, v143, v143 op_sel_hi:[0,0,0]
	v_mfma_scale_f32_16x16x128_f8f6f4 v[104:107], v[152:159], v[184:191], 0, v143, v143 op_sel_hi:[0,0,0]
	v_mfma_scale_f32_16x16x128_f8f6f4 v[96:99], v[144:151], v[192:199], 0, v143, v143 op_sel_hi:[0,0,0]
	v_mfma_scale_f32_16x16x128_f8f6f4 v[130:133], v[152:159], v[192:199], 0, v143, v143 op_sel_hi:[0,0,0]
	v_mfma_scale_f32_16x16x128_f8f6f4 v[208:211], v[144:151], v[200:207], 0, v143, v143 op_sel_hi:[0,0,0]
	v_mfma_scale_f32_16x16x128_f8f6f4 v[212:215], v[152:159], v[200:207], 0, v143, v143 op_sel_hi:[0,0,0]
	s_setprio 0
	s_setprio 1
	v_mfma_scale_f32_16x16x128_f8f6f4 v[116:119], v[160:167], v[176:183], 0, v143, v143 op_sel_hi:[0,0,0]
	v_mfma_scale_f32_16x16x128_f8f6f4 v[108:111], v[168:175], v[176:183], 0, v143, v143 op_sel_hi:[0,0,0]
	v_mfma_scale_f32_16x16x128_f8f6f4 v[100:103], v[160:167], v[184:191], 0, v143, v143 op_sel_hi:[0,0,0]
	v_mfma_scale_f32_16x16x128_f8f6f4 v[176:179], v[168:175], v[184:191], 0, v143, v143 op_sel_hi:[0,0,0]
	v_mfma_scale_f32_16x16x128_f8f6f4 v[180:183], v[160:167], v[192:199], 0, v143, v143 op_sel_hi:[0,0,0]
	v_mfma_scale_f32_16x16x128_f8f6f4 v[184:187], v[168:175], v[192:199], 0, v143, v143 op_sel_hi:[0,0,0]
	v_mfma_scale_f32_16x16x128_f8f6f4 v[188:191], v[160:167], v[200:207], 0, v143, v143 op_sel_hi:[0,0,0]
	v_mfma_scale_f32_16x16x128_f8f6f4 v[192:195], v[168:175], v[200:207], 0, v143, v143 op_sel_hi:[0,0,0]
	s_setprio 0
	s_waitcnt vmcnt(8)
	s_barrier
	s_add_i32 s63, s53, s3
	v_mov_b32_e32 v128, v138
	v_mov_b32_e32 v196, v137
	s_mov_b32 m0, s63
	s_nop 0
	ds_read_b128 v[64:67], v142 offset:16384
	ds_read_b128 v[68:71], v142 offset:17408
	ds_read_b128 v[72:75], v142 offset:18432
	ds_read_b128 v[76:79], v142 offset:19456
	ds_read_b128 v[80:83], v142 offset:20480
	ds_read_b128 v[84:87], v142 offset:21504
	ds_read_b128 v[88:91], v142 offset:22528
	ds_read_b128 v[92:95], v142 offset:23552
	v_mov_b32_e32 v197, v129
	global_load_lds_dwordx4 v196, s[34:35]
	s_add_i32 m0, s63, 0x2000
	v_mov_b32_e32 v196, v138
	global_load_lds_dwordx4 v128, s[34:35]
	v_mov_b32_e32 v128, v137
	s_add_i32 s63, s54, s3
	v_lshl_add_u64 v[198:199], s[34:35], 0, v[128:129]
	v_lshl_add_u64 v[198:199], v[198:199], 0, s[8:9]
	s_mov_b32 m0, s63
	v_lshl_add_u64 v[196:197], s[34:35], 0, v[196:197]
	global_load_lds_dwordx4 v[198:199], off
	v_lshl_add_u64 v[196:197], v[196:197], 0, s[8:9]
	s_add_i32 m0, s63, 0x2000
	v_mov_b32_e32 v128, v136
	global_load_lds_dwordx4 v[196:197], off
	v_mov_b32_e32 v196, v135
	s_mov_b32 m0, s40
	s_nop 0
	global_load_lds_dwordx4 v196, s[30:31]
	s_mov_b32 m0, s41
	s_nop 0
	global_load_lds_dwordx4 v128, s[30:31]
	s_and_b64 vcc, exec, s[14:15]
	s_cbranch_vccnz .Lmy_p2lw_10
	s_waitcnt vmcnt(8)
.Lmy_p2lw_10:
	s_waitcnt lgkmcnt(0)
	s_barrier
	s_setprio 1
	s_waitcnt lgkmcnt(0)
	v_mfma_scale_f32_16x16x128_f8f6f4 v[60:63], v[144:151], v[64:71], 0, v143, v143 op_sel_hi:[0,0,0]
	v_mfma_scale_f32_16x16x128_f8f6f4 v[56:59], v[152:159], v[64:71], 0, v143, v143 op_sel_hi:[0,0,0]
	v_mfma_scale_f32_16x16x128_f8f6f4 v[48:51], v[144:151], v[72:79], 0, v143, v143 op_sel_hi:[0,0,0]
	v_mfma_scale_f32_16x16x128_f8f6f4 v[196:199], v[152:159], v[72:79], 0, v143, v143 op_sel_hi:[0,0,0]
	v_mfma_scale_f32_16x16x128_f8f6f4 v[200:203], v[144:151], v[80:87], 0, v143, v143 op_sel_hi:[0,0,0]
	v_mfma_scale_f32_16x16x128_f8f6f4 v[204:207], v[152:159], v[80:87], 0, v143, v143 op_sel_hi:[0,0,0]
	v_mfma_scale_f32_16x16x128_f8f6f4 v[216:219], v[144:151], v[88:95], 0, v143, v143 op_sel_hi:[0,0,0]
	v_mfma_scale_f32_16x16x128_f8f6f4 v[220:223], v[152:159], v[88:95], 0, v143, v143 op_sel_hi:[0,0,0]
	s_setprio 0
	s_setprio 1
	v_mfma_scale_f32_16x16x128_f8f6f4 v[52:55], v[160:167], v[64:71], 0, v143, v143 op_sel_hi:[0,0,0]
	v_mfma_scale_f32_16x16x128_f8f6f4 v[224:227], v[168:175], v[64:71], 0, v143, v143 op_sel_hi:[0,0,0]
	v_mfma_scale_f32_16x16x128_f8f6f4 v[228:231], v[160:167], v[72:79], 0, v143, v143 op_sel_hi:[0,0,0]
	v_mfma_scale_f32_16x16x128_f8f6f4 v[232:235], v[168:175], v[72:79], 0, v143, v143 op_sel_hi:[0,0,0]
	v_mfma_scale_f32_16x16x128_f8f6f4 v[236:239], v[160:167], v[80:87], 0, v143, v143 op_sel_hi:[0,0,0]
	v_mfma_scale_f32_16x16x128_f8f6f4 v[240:243], v[168:175], v[80:87], 0, v143, v143 op_sel_hi:[0,0,0]
	v_mfma_scale_f32_16x16x128_f8f6f4 v[244:247], v[160:167], v[88:95], 0, v143, v143 op_sel_hi:[0,0,0]
	v_mfma_scale_f32_16x16x128_f8f6f4 v[248:251], v[168:175], v[88:95], 0, v143, v143 op_sel_hi:[0,0,0]
	s_setprio 0
	s_waitcnt vmcnt(8)
	s_barrier
	s_add_i32 s63, 0, 0x18000
	s_add_i32 s66, 0, 0x1c000
	s_nop 0
	v_add_u32_e32 v12, s63, v139
	v_add_u32_e32 v16, s66, v139
	ds_read_b128 v[0:3], v12
	ds_read_b128 v[4:7], v12 offset:1024
	ds_read_b128 v[8:11], v12 offset:2048
	ds_read_b128 v[12:15], v12 offset:3072
	ds_read_b128 v[144:147], v16
	ds_read_b128 v[148:151], v16 offset:1024
	ds_read_b128 v[152:155], v16 offset:2048
	ds_read_b128 v[156:159], v16 offset:3072
	s_add_u32 s64, s30, 0x40000
	v_mov_b32_e32 v64, v136
	v_mov_b32_e32 v65, v135
	s_addc_u32 s65, s31, 0
	s_mov_b32 m0, s42
	ds_read_b128 v[16:19], v142 offset:32768
	ds_read_b128 v[20:23], v142 offset:33792
	ds_read_b128 v[24:27], v142 offset:34816
	ds_read_b128 v[28:31], v142 offset:35840
	ds_read_b128 v[32:35], v142 offset:36864
	ds_read_b128 v[36:39], v142 offset:37888
	ds_read_b128 v[40:43], v142 offset:38912
	ds_read_b128 v[44:47], v142 offset:39936
	s_nop 0
	global_load_lds_dwordx4 v65, s[64:65]
	s_mov_b32 m0, s43
	s_nop 0
	global_load_lds_dwordx4 v64, s[64:65]
	s_and_b64 vcc, exec, s[14:15]
	s_cbranch_vccnz .Lmy_p2lw_11
	s_waitcnt vmcnt(8)

.Lmy_p2lw_12:
	s_waitcnt lgkmcnt(0)
	s_barrier
	s_setprio 1
	s_waitcnt lgkmcnt(0)
	v_mfma_scale_f32_16x16x128_f8f6f4 v[60:63], v[0:7], v[160:167], v[60:63], v143, v143 op_sel_hi:[0,0,0]
	v_mfma_scale_f32_16x16x128_f8f6f4 v[56:59], v[8:15], v[160:167], v[56:59], v143, v143 op_sel_hi:[0,0,0]
	v_mfma_scale_f32_16x16x128_f8f6f4 v[48:51], v[0:7], v[168:175], v[48:51], v143, v143 op_sel_hi:[0,0,0]
	v_mfma_scale_f32_16x16x128_f8f6f4 v[40:43], v[8:15], v[168:175], v[196:199], v143, v143 op_sel_hi:[0,0,0]
	v_mfma_scale_f32_16x16x128_f8f6f4 v[32:35], v[0:7], v[176:183], v[200:203], v143, v143 op_sel_hi:[0,0,0]
	v_mfma_scale_f32_16x16x128_f8f6f4 v[24:27], v[8:15], v[176:183], v[204:207], v143, v143 op_sel_hi:[0,0,0]
	v_mfma_scale_f32_16x16x128_f8f6f4 v[16:19], v[0:7], v[184:191], v[216:219], v143, v143 op_sel_hi:[0,0,0]
	v_mfma_scale_f32_16x16x128_f8f6f4 v[8:11], v[8:15], v[184:191], v[220:223], v143, v143 op_sel_hi:[0,0,0]
	s_setprio 0
	s_setprio 1
	v_mfma_scale_f32_16x16x128_f8f6f4 v[52:55], v[144:151], v[160:167], v[52:55], v143, v143 op_sel_hi:[0,0,0]
	v_mfma_scale_f32_16x16x128_f8f6f4 v[44:47], v[152:159], v[160:167], v[224:227], v143, v143 op_sel_hi:[0,0,0]
	v_mfma_scale_f32_16x16x128_f8f6f4 v[36:39], v[144:151], v[168:175], v[228:231], v143, v143 op_sel_hi:[0,0,0]
	v_mfma_scale_f32_16x16x128_f8f6f4 v[28:31], v[152:159], v[168:175], v[232:235], v143, v143 op_sel_hi:[0,0,0]
	v_mfma_scale_f32_16x16x128_f8f6f4 v[20:23], v[144:151], v[176:183], v[236:239], v143, v143 op_sel_hi:[0,0,0]
	v_mfma_scale_f32_16x16x128_f8f6f4 v[12:15], v[152:159], v[176:183], v[240:243], v143, v143 op_sel_hi:[0,0,0]
	v_mfma_scale_f32_16x16x128_f8f6f4 v[4:7], v[144:151], v[184:191], v[244:247], v143, v143 op_sel_hi:[0,0,0]
	v_mfma_scale_f32_16x16x128_f8f6f4 v[0:3], v[152:159], v[184:191], v[248:251], v143, v143 op_sel_hi:[0,0,0]
	s_setprio 0
	s_waitcnt vmcnt(8)
	s_barrier
	s_add_i32 s49, s49, 2
	s_add_u32 s19, s19, 0x80000
	s_addc_u32 s48, s48, 0
	s_add_u32 s28, s28, 0x100
	s_addc_u32 s29, s29, 0
	s_cmp_gt_u32 s49, 13
.LBB0_1751:
	ds_read_b128 v[144:147], v140
	ds_read_b128 v[148:151], v140 offset:1024
	ds_read_b128 v[152:155], v140 offset:2048
	ds_read_b128 v[156:159], v140 offset:3072
	ds_read_b128 v[160:163], v141
	ds_read_b128 v[164:167], v141 offset:1024
	ds_read_b128 v[168:171], v141 offset:2048
	ds_read_b128 v[172:175], v141 offset:3072
	s_add_u32 s30, s28, 0xfffc0080
	s_addc_u32 s31, s29, -1
	s_cmp_eq_u32 s49, 12
	s_cselect_b32 s31, s21, s31
	s_cselect_b32 s30, s20, s30
	s_cselect_b32 s35, s23, s48
	s_cselect_b32 s34, s22, s19
	v_mov_b32_e32 v128, v136
	v_mov_b32_e32 v130, v135
	s_add_i32 m0, s40, 0xc000
	ds_read_b128 v[176:179], v142
	ds_read_b128 v[180:183], v142 offset:1024
	ds_read_b128 v[184:187], v142 offset:2048
	ds_read_b128 v[188:191], v142 offset:3072
	ds_read_b128 v[192:195], v142 offset:4096
	ds_read_b128 v[196:199], v142 offset:5120
	ds_read_b128 v[200:203], v142 offset:6144
	ds_read_b128 v[204:207], v142 offset:7168
	s_nop 0
	global_load_lds_dwordx4 v130, s[28:29]
	s_add_i32 m0, s40, 0xe000
	s_nop 0
	global_load_lds_dwordx4 v128, s[28:29]
	s_and_b64 vcc, exec, s[14:15]
	s_cbranch_vccnz .Lmy_lw_9
	s_waitcnt vmcnt(8)

.LBB0_2892:
	s_add_u32 s21, s34, 0x100000
	s_addc_u32 s53, s35, 0
	s_add_u32 s30, s30, 0x40080
	s_addc_u32 s31, s31, 0
	s_mov_b32 s54, -2
	ds_read_b128 v[142:145], v138
	ds_read_b128 v[146:149], v138 offset:1024
	ds_read_b128 v[150:153], v138 offset:2048
	ds_read_b128 v[154:157], v138 offset:3072
	ds_read_b128 v[158:161], v139
	ds_read_b128 v[162:165], v139 offset:1024
	ds_read_b128 v[166:169], v139 offset:2048
	ds_read_b128 v[170:173], v139 offset:3072
	s_add_u32 s34, s30, 0xfffc0080
	s_addc_u32 s35, s31, -1
	s_cmp_eq_u32 s54, 12
	s_cselect_b32 s35, s23, s35
	s_cselect_b32 s34, s22, s34
	s_cselect_b32 s37, s25, s53
	s_cselect_b32 s36, s24, s21
	v_mov_b32_e32 v128, v133
	v_mov_b32_e32 v130, v134
	s_add_i32 m0, s41, 0xc000
	ds_read_b128 v[174:177], v140
	ds_read_b128 v[178:181], v140 offset:1024
	ds_read_b128 v[182:185], v140 offset:2048
	ds_read_b128 v[186:189], v140 offset:3072
	ds_read_b128 v[190:193], v140 offset:4096
	ds_read_b128 v[194:197], v140 offset:5120
	ds_read_b128 v[198:201], v140 offset:6144
	ds_read_b128 v[202:205], v140 offset:7168
	s_nop 0
	global_load_lds_dwordx4 v128, s[30:31]
	s_add_i32 m0, s41, 0xe000
	s_nop 0
	global_load_lds_dwordx4 v130, s[30:31]
	s_and_b64 vcc, exec, s[14:15]
	s_cbranch_vccnz .Lmy_p3lw_17
	s_waitcnt vmcnt(8)
.Lmy_p3lw_17:
	s_waitcnt lgkmcnt(0)
	s_barrier
	s_setprio 1
	s_waitcnt lgkmcnt(0)
	v_mfma_scale_f32_16x16x128_f8f6f4 v[124:127], v[142:149], v[174:181], 0, v141, v141 op_sel_hi:[0,0,0]
	v_mfma_scale_f32_16x16x128_f8f6f4 v[116:119], v[150:157], v[174:181], 0, v141, v141 op_sel_hi:[0,0,0]
	v_mfma_scale_f32_16x16x128_f8f6f4 v[108:111], v[142:149], v[182:189], 0, v141, v141 op_sel_hi:[0,0,0]
	v_mfma_scale_f32_16x16x128_f8f6f4 v[100:103], v[150:157], v[182:189], 0, v141, v141 op_sel_hi:[0,0,0]
	v_mfma_scale_f32_16x16x128_f8f6f4 v[206:209], v[142:149], v[190:197], 0, v141, v141 op_sel_hi:[0,0,0]
	v_mfma_scale_f32_16x16x128_f8f6f4 v[210:213], v[150:157], v[190:197], 0, v141, v141 op_sel_hi:[0,0,0]
	v_mfma_scale_f32_16x16x128_f8f6f4 v[214:217], v[142:149], v[198:205], 0, v141, v141 op_sel_hi:[0,0,0]
	v_mfma_scale_f32_16x16x128_f8f6f4 v[218:221], v[150:157], v[198:205], 0, v141, v141 op_sel_hi:[0,0,0]
	s_setprio 0
	s_setprio 1
	v_mfma_scale_f32_16x16x128_f8f6f4 v[120:123], v[158:165], v[174:181], 0, v141, v141 op_sel_hi:[0,0,0]
	v_mfma_scale_f32_16x16x128_f8f6f4 v[112:115], v[166:173], v[174:181], 0, v141, v141 op_sel_hi:[0,0,0]
	v_mfma_scale_f32_16x16x128_f8f6f4 v[104:107], v[158:165], v[182:189], 0, v141, v141 op_sel_hi:[0,0,0]
	v_mfma_scale_f32_16x16x128_f8f6f4 v[96:99], v[166:173], v[182:189], 0, v141, v141 op_sel_hi:[0,0,0]
	v_mfma_scale_f32_16x16x128_f8f6f4 v[174:177], v[158:165], v[190:197], 0, v141, v141 op_sel_hi:[0,0,0]
	v_mfma_scale_f32_16x16x128_f8f6f4 v[178:181], v[166:173], v[190:197], 0, v141, v141 op_sel_hi:[0,0,0]
	v_mfma_scale_f32_16x16x128_f8f6f4 v[182:185], v[158:165], v[198:205], 0, v141, v141 op_sel_hi:[0,0,0]
	v_mfma_scale_f32_16x16x128_f8f6f4 v[186:189], v[166:173], v[198:205], 0, v141, v141 op_sel_hi:[0,0,0]
	s_setprio 0
	s_waitcnt vmcnt(8)
	s_barrier
	s_add_i32 s55, s50, s3
	v_mov_b32_e32 v128, v135
	v_mov_b32_e32 v130, v136
	s_mov_b32 m0, s55
	s_nop 0
	ds_read_b128 v[64:67], v140 offset:16384
	ds_read_b128 v[68:71], v140 offset:17408
	ds_read_b128 v[72:75], v140 offset:18432
	ds_read_b128 v[76:79], v140 offset:19456
	ds_read_b128 v[80:83], v140 offset:20480
	ds_read_b128 v[84:87], v140 offset:21504
	ds_read_b128 v[88:91], v140 offset:22528
	ds_read_b128 v[92:95], v140 offset:23552
	v_mov_b32_e32 v131, v129
	global_load_lds_dwordx4 v128, s[36:37]
	s_add_i32 m0, s55, 0x2000
	v_mov_b32_e32 v128, v135
	global_load_lds_dwordx4 v130, s[36:37]
	v_mov_b32_e32 v130, v136
	s_add_i32 s55, s51, s3
	v_lshl_add_u64 v[190:191], s[36:37], 0, v[128:129]
	v_lshl_add_u64 v[190:191], v[190:191], 0, s[8:9]
	s_mov_b32 m0, s55
	v_lshl_add_u64 v[130:131], s[36:37], 0, v[130:131]
	global_load_lds_dwordx4 v[190:191], off
	v_lshl_add_u64 v[130:131], v[130:131], 0, s[8:9]
	s_add_i32 m0, s55, 0x2000
	v_mov_b32_e32 v128, v133
	global_load_lds_dwordx4 v[130:131], off
	v_mov_b32_e32 v130, v134
	s_mov_b32 m0, s41
	s_nop 0
	global_load_lds_dwordx4 v128, s[34:35]
	s_mov_b32 m0, s42
	s_nop 0
	global_load_lds_dwordx4 v130, s[34:35]
	s_and_b64 vcc, exec, s[14:15]
	s_cbranch_vccnz .Lmy_p3lw_18
	s_waitcnt vmcnt(8)
.Lmy_p3lw_18:
	s_waitcnt lgkmcnt(0)
	s_barrier
	s_setprio 1
	s_waitcnt lgkmcnt(0)
	v_mfma_scale_f32_16x16x128_f8f6f4 v[60:63], v[142:149], v[64:71], 0, v141, v141 op_sel_hi:[0,0,0]
	v_mfma_scale_f32_16x16x128_f8f6f4 v[52:55], v[150:157], v[64:71], 0, v141, v141 op_sel_hi:[0,0,0]
	v_mfma_scale_f32_16x16x128_f8f6f4 v[44:47], v[142:149], v[72:79], 0, v141, v141 op_sel_hi:[0,0,0]
	v_mfma_scale_f32_16x16x128_f8f6f4 v[198:201], v[150:157], v[72:79], 0, v141, v141 op_sel_hi:[0,0,0]
	v_mfma_scale_f32_16x16x128_f8f6f4 v[202:205], v[142:149], v[80:87], 0, v141, v141 op_sel_hi:[0,0,0]
	v_mfma_scale_f32_16x16x128_f8f6f4 v[222:225], v[150:157], v[80:87], 0, v141, v141 op_sel_hi:[0,0,0]
	v_mfma_scale_f32_16x16x128_f8f6f4 v[226:229], v[142:149], v[88:95], 0, v141, v141 op_sel_hi:[0,0,0]
	v_mfma_scale_f32_16x16x128_f8f6f4 v[230:233], v[150:157], v[88:95], 0, v141, v141 op_sel_hi:[0,0,0]
	s_setprio 0
	s_setprio 1
	v_mfma_scale_f32_16x16x128_f8f6f4 v[56:59], v[158:165], v[64:71], 0, v141, v141 op_sel_hi:[0,0,0]
	v_mfma_scale_f32_16x16x128_f8f6f4 v[48:51], v[166:173], v[64:71], 0, v141, v141 op_sel_hi:[0,0,0]
	v_mfma_scale_f32_16x16x128_f8f6f4 v[40:43], v[158:165], v[72:79], 0, v141, v141 op_sel_hi:[0,0,0]
	v_mfma_scale_f32_16x16x128_f8f6f4 v[234:237], v[166:173], v[72:79], 0, v141, v141 op_sel_hi:[0,0,0]
	v_mfma_scale_f32_16x16x128_f8f6f4 v[238:241], v[158:165], v[80:87], 0, v141, v141 op_sel_hi:[0,0,0]
	v_mfma_scale_f32_16x16x128_f8f6f4 v[242:245], v[166:173], v[80:87], 0, v141, v141 op_sel_hi:[0,0,0]
	v_mfma_scale_f32_16x16x128_f8f6f4 v[246:249], v[158:165], v[88:95], 0, v141, v141 op_sel_hi:[0,0,0]
	v_mfma_scale_f32_16x16x128_f8f6f4 v[250:253], v[166:173], v[88:95], 0, v141, v141 op_sel_hi:[0,0,0]
	s_setprio 0
	s_waitcnt vmcnt(8)
	s_barrier
	s_add_i32 s55, 0, 0x18000
	s_nop 2
	v_add_u32_e32 v8, s55, v137
	s_add_i32 s63, 0, 0x1c000
	ds_read_b128 v[0:3], v8
	ds_read_b128 v[4:7], v8 offset:1024
	ds_read_b128 v[142:145], v8 offset:2048
	ds_read_b128 v[146:149], v8 offset:3072
	v_add_u32_e32 v8, s63, v137
	ds_read_b128 v[150:153], v8
	ds_read_b128 v[154:157], v8 offset:1024
	ds_read_b128 v[158:161], v8 offset:2048
	ds_read_b128 v[162:165], v8 offset:3072
	s_add_u32 s64, s34, 0x40000
	v_mov_b32_e32 v64, v133
	v_mov_b32_e32 v65, v134
	s_addc_u32 s65, s35, 0
	s_mov_b32 m0, s43
	ds_read_b128 v[8:11], v140 offset:32768
	ds_read_b128 v[12:15], v140 offset:33792
	ds_read_b128 v[16:19], v140 offset:34816
	ds_read_b128 v[20:23], v140 offset:35840
	ds_read_b128 v[24:27], v140 offset:36864
	ds_read_b128 v[28:31], v140 offset:37888
	ds_read_b128 v[32:35], v140 offset:38912
	ds_read_b128 v[36:39], v140 offset:39936
	s_nop 0
	global_load_lds_dwordx4 v64, s[64:65]
	s_mov_b32 m0, s44
	s_nop 0
	global_load_lds_dwordx4 v65, s[64:65]
	s_and_b64 vcc, exec, s[14:15]
	s_cbranch_vccnz .Lmy_p3lw_19
	s_waitcnt vmcnt(8)

.Lmy_p3lw_20:
	s_waitcnt lgkmcnt(0)
	s_barrier
	s_setprio 1
	s_waitcnt lgkmcnt(0)
	v_mfma_scale_f32_16x16x128_f8f6f4 v[60:63], v[0:7], v[166:173], v[60:63], v141, v141 op_sel_hi:[0,0,0]
	v_mfma_scale_f32_16x16x128_f8f6f4 v[52:55], v[142:149], v[166:173], v[52:55], v141, v141 op_sel_hi:[0,0,0]
	v_mfma_scale_f32_16x16x128_f8f6f4 v[44:47], v[0:7], v[174:181], v[44:47], v141, v141 op_sel_hi:[0,0,0]
	v_mfma_scale_f32_16x16x128_f8f6f4 v[36:39], v[142:149], v[174:181], v[198:201], v141, v141 op_sel_hi:[0,0,0]
	v_mfma_scale_f32_16x16x128_f8f6f4 v[28:31], v[0:7], v[182:189], v[202:205], v141, v141 op_sel_hi:[0,0,0]
	v_mfma_scale_f32_16x16x128_f8f6f4 v[20:23], v[142:149], v[182:189], v[222:225], v141, v141 op_sel_hi:[0,0,0]
	v_mfma_scale_f32_16x16x128_f8f6f4 v[12:15], v[0:7], v[190:197], v[226:229], v141, v141 op_sel_hi:[0,0,0]
	v_mfma_scale_f32_16x16x128_f8f6f4 v[4:7], v[142:149], v[190:197], v[230:233], v141, v141 op_sel_hi:[0,0,0]
	s_setprio 0
	s_setprio 1
	v_mfma_scale_f32_16x16x128_f8f6f4 v[56:59], v[150:157], v[166:173], v[56:59], v141, v141 op_sel_hi:[0,0,0]
	v_mfma_scale_f32_16x16x128_f8f6f4 v[48:51], v[158:165], v[166:173], v[48:51], v141, v141 op_sel_hi:[0,0,0]
	v_mfma_scale_f32_16x16x128_f8f6f4 v[40:43], v[150:157], v[174:181], v[40:43], v141, v141 op_sel_hi:[0,0,0]
	v_mfma_scale_f32_16x16x128_f8f6f4 v[32:35], v[158:165], v[174:181], v[234:237], v141, v141 op_sel_hi:[0,0,0]
	v_mfma_scale_f32_16x16x128_f8f6f4 v[24:27], v[150:157], v[182:189], v[238:241], v141, v141 op_sel_hi:[0,0,0]
	v_mfma_scale_f32_16x16x128_f8f6f4 v[16:19], v[158:165], v[182:189], v[242:245], v141, v141 op_sel_hi:[0,0,0]
	v_mfma_scale_f32_16x16x128_f8f6f4 v[8:11], v[150:157], v[190:197], v[246:249], v141, v141 op_sel_hi:[0,0,0]
	v_mfma_scale_f32_16x16x128_f8f6f4 v[0:3], v[158:165], v[190:197], v[250:253], v141, v141 op_sel_hi:[0,0,0]
	s_setprio 0
	s_waitcnt vmcnt(8)
	s_barrier
	s_add_i32 s54, s54, 2
	s_add_u32 s21, s21, 0x100000
	s_addc_u32 s53, s53, 0
	s_add_u32 s30, s30, 0x100
	s_addc_u32 s31, s31, 0
	s_cmp_gt_u32 s54, 13
.LBB0_2893:
	ds_read_b128 v[142:145], v138
	ds_read_b128 v[146:149], v138 offset:1024
	ds_read_b128 v[150:153], v138 offset:2048
	ds_read_b128 v[154:157], v138 offset:3072
	ds_read_b128 v[158:161], v139
	ds_read_b128 v[162:165], v139 offset:1024
	ds_read_b128 v[166:169], v139 offset:2048
	ds_read_b128 v[170:173], v139 offset:3072
	s_add_u32 s34, s30, 0xfffc0080
	s_addc_u32 s35, s31, -1
	s_cmp_eq_u32 s54, 12
	s_cselect_b32 s35, s23, s35
	s_cselect_b32 s34, s22, s34
	s_cselect_b32 s37, s25, s53
	s_cselect_b32 s36, s24, s21
	v_mov_b32_e32 v128, v133
	v_mov_b32_e32 v130, v134
	s_add_i32 m0, s41, 0xc000
	ds_read_b128 v[174:177], v140
	ds_read_b128 v[178:181], v140 offset:1024
	ds_read_b128 v[182:185], v140 offset:2048
	ds_read_b128 v[186:189], v140 offset:3072
	ds_read_b128 v[190:193], v140 offset:4096
	ds_read_b128 v[194:197], v140 offset:5120
	ds_read_b128 v[198:201], v140 offset:6144
	ds_read_b128 v[202:205], v140 offset:7168
	s_nop 0
	global_load_lds_dwordx4 v128, s[30:31]
	s_add_i32 m0, s41, 0xe000
	s_nop 0
	global_load_lds_dwordx4 v130, s[30:31]
	s_and_b64 vcc, exec, s[14:15]
	s_cbranch_vccnz .Lmy_lw_17
	s_waitcnt vmcnt(8)

.LBB0_2963:
	s_add_u32 s19, s30, 0x80000
	s_addc_u32 s52, s31, 0
	s_add_u32 s28, s28, 0x40080
	s_addc_u32 s29, s29, 0
	s_mov_b32 s53, -2
	ds_read_b128 v[144:147], v140
	ds_read_b128 v[148:151], v140 offset:1024
	ds_read_b128 v[152:155], v140 offset:2048
	ds_read_b128 v[156:159], v140 offset:3072
	ds_read_b128 v[160:163], v141
	ds_read_b128 v[164:167], v141 offset:1024
	ds_read_b128 v[168:171], v141 offset:2048
	ds_read_b128 v[172:175], v141 offset:3072
	s_add_u32 s30, s28, 0xfffc0080
	s_addc_u32 s31, s29, -1
	s_cmp_eq_u32 s53, 12
	s_cselect_b32 s31, s21, s31
	s_cselect_b32 s30, s20, s30
	s_cselect_b32 s35, s23, s52
	s_cselect_b32 s34, s22, s19
	v_mov_b32_e32 v128, v135
	v_mov_b32_e32 v130, v136
	s_add_i32 m0, s40, 0xc000
	ds_read_b128 v[176:179], v142
	ds_read_b128 v[180:183], v142 offset:1024
	ds_read_b128 v[184:187], v142 offset:2048
	ds_read_b128 v[188:191], v142 offset:3072
	ds_read_b128 v[192:195], v142 offset:4096
	ds_read_b128 v[196:199], v142 offset:5120
	ds_read_b128 v[200:203], v142 offset:6144
	ds_read_b128 v[204:207], v142 offset:7168
	s_nop 0
	global_load_lds_dwordx4 v128, s[28:29]
	s_add_i32 m0, s40, 0xe000
	s_nop 0
	global_load_lds_dwordx4 v130, s[28:29]
	s_and_b64 vcc, exec, s[14:15]
	s_cbranch_vccnz .Lmy_p4lw_21
	s_waitcnt vmcnt(8)
.Lmy_p4lw_21:
	s_waitcnt lgkmcnt(0)
	s_barrier
	s_setprio 1
	s_waitcnt lgkmcnt(0)
	v_mfma_scale_f32_16x16x128_f8f6f4 v[124:127], v[144:151], v[176:183], 0, v143, v143 op_sel_hi:[0,0,0]
	v_mfma_scale_f32_16x16x128_f8f6f4 v[120:123], v[152:159], v[176:183], 0, v143, v143 op_sel_hi:[0,0,0]
	v_mfma_scale_f32_16x16x128_f8f6f4 v[112:115], v[144:151], v[184:191], 0, v143, v143 op_sel_hi:[0,0,0]
	v_mfma_scale_f32_16x16x128_f8f6f4 v[104:107], v[152:159], v[184:191], 0, v143, v143 op_sel_hi:[0,0,0]
	v_mfma_scale_f32_16x16x128_f8f6f4 v[96:99], v[144:151], v[192:199], 0, v143, v143 op_sel_hi:[0,0,0]
	v_mfma_scale_f32_16x16x128_f8f6f4 v[130:133], v[152:159], v[192:199], 0, v143, v143 op_sel_hi:[0,0,0]
	v_mfma_scale_f32_16x16x128_f8f6f4 v[208:211], v[144:151], v[200:207], 0, v143, v143 op_sel_hi:[0,0,0]
	v_mfma_scale_f32_16x16x128_f8f6f4 v[212:215], v[152:159], v[200:207], 0, v143, v143 op_sel_hi:[0,0,0]
	s_setprio 0
	s_setprio 1
	v_mfma_scale_f32_16x16x128_f8f6f4 v[116:119], v[160:167], v[176:183], 0, v143, v143 op_sel_hi:[0,0,0]
	v_mfma_scale_f32_16x16x128_f8f6f4 v[108:111], v[168:175], v[176:183], 0, v143, v143 op_sel_hi:[0,0,0]
	v_mfma_scale_f32_16x16x128_f8f6f4 v[100:103], v[160:167], v[184:191], 0, v143, v143 op_sel_hi:[0,0,0]
	v_mfma_scale_f32_16x16x128_f8f6f4 v[176:179], v[168:175], v[184:191], 0, v143, v143 op_sel_hi:[0,0,0]
	v_mfma_scale_f32_16x16x128_f8f6f4 v[180:183], v[160:167], v[192:199], 0, v143, v143 op_sel_hi:[0,0,0]
	v_mfma_scale_f32_16x16x128_f8f6f4 v[184:187], v[168:175], v[192:199], 0, v143, v143 op_sel_hi:[0,0,0]
	v_mfma_scale_f32_16x16x128_f8f6f4 v[188:191], v[160:167], v[200:207], 0, v143, v143 op_sel_hi:[0,0,0]
	v_mfma_scale_f32_16x16x128_f8f6f4 v[192:195], v[168:175], v[200:207], 0, v143, v143 op_sel_hi:[0,0,0]
	s_setprio 0
	s_waitcnt vmcnt(8)
	s_barrier
	s_add_i32 s54, s49, s3
	v_mov_b32_e32 v128, v137
	v_mov_b32_e32 v196, v138
	s_mov_b32 m0, s54
	s_nop 0
	ds_read_b128 v[64:67], v142 offset:16384
	ds_read_b128 v[68:71], v142 offset:17408
	ds_read_b128 v[72:75], v142 offset:18432
	ds_read_b128 v[76:79], v142 offset:19456
	ds_read_b128 v[80:83], v142 offset:20480
	ds_read_b128 v[84:87], v142 offset:21504
	ds_read_b128 v[88:91], v142 offset:22528
	ds_read_b128 v[92:95], v142 offset:23552
	v_mov_b32_e32 v197, v129
	global_load_lds_dwordx4 v128, s[34:35]
	s_add_i32 m0, s54, 0x2000
	v_mov_b32_e32 v128, v137
	global_load_lds_dwordx4 v196, s[34:35]
	v_mov_b32_e32 v196, v138
	s_add_i32 s54, s50, s3
	v_lshl_add_u64 v[198:199], s[34:35], 0, v[128:129]
	v_lshl_add_u64 v[198:199], v[198:199], 0, s[8:9]
	s_mov_b32 m0, s54
	v_lshl_add_u64 v[196:197], s[34:35], 0, v[196:197]
	global_load_lds_dwordx4 v[198:199], off
	v_lshl_add_u64 v[196:197], v[196:197], 0, s[8:9]
	s_add_i32 m0, s54, 0x2000
	v_mov_b32_e32 v128, v135
	global_load_lds_dwordx4 v[196:197], off
	v_mov_b32_e32 v196, v136
	s_mov_b32 m0, s40
	s_nop 0
	global_load_lds_dwordx4 v128, s[30:31]
	s_mov_b32 m0, s41
	s_nop 0
	global_load_lds_dwordx4 v196, s[30:31]
	s_and_b64 vcc, exec, s[14:15]
	s_cbranch_vccnz .Lmy_p4lw_22
	s_waitcnt vmcnt(8)
.Lmy_p4lw_22:
	s_waitcnt lgkmcnt(0)
	s_barrier
	s_setprio 1
	s_waitcnt lgkmcnt(0)
	v_mfma_scale_f32_16x16x128_f8f6f4 v[60:63], v[144:151], v[64:71], 0, v143, v143 op_sel_hi:[0,0,0]
	v_mfma_scale_f32_16x16x128_f8f6f4 v[56:59], v[152:159], v[64:71], 0, v143, v143 op_sel_hi:[0,0,0]
	v_mfma_scale_f32_16x16x128_f8f6f4 v[48:51], v[144:151], v[72:79], 0, v143, v143 op_sel_hi:[0,0,0]
	v_mfma_scale_f32_16x16x128_f8f6f4 v[196:199], v[152:159], v[72:79], 0, v143, v143 op_sel_hi:[0,0,0]
	v_mfma_scale_f32_16x16x128_f8f6f4 v[200:203], v[144:151], v[80:87], 0, v143, v143 op_sel_hi:[0,0,0]
	v_mfma_scale_f32_16x16x128_f8f6f4 v[204:207], v[152:159], v[80:87], 0, v143, v143 op_sel_hi:[0,0,0]
	v_mfma_scale_f32_16x16x128_f8f6f4 v[216:219], v[144:151], v[88:95], 0, v143, v143 op_sel_hi:[0,0,0]
	v_mfma_scale_f32_16x16x128_f8f6f4 v[220:223], v[152:159], v[88:95], 0, v143, v143 op_sel_hi:[0,0,0]
	s_setprio 0
	s_setprio 1
	v_mfma_scale_f32_16x16x128_f8f6f4 v[52:55], v[160:167], v[64:71], 0, v143, v143 op_sel_hi:[0,0,0]
	v_mfma_scale_f32_16x16x128_f8f6f4 v[224:227], v[168:175], v[64:71], 0, v143, v143 op_sel_hi:[0,0,0]
	v_mfma_scale_f32_16x16x128_f8f6f4 v[228:231], v[160:167], v[72:79], 0, v143, v143 op_sel_hi:[0,0,0]
	v_mfma_scale_f32_16x16x128_f8f6f4 v[232:235], v[168:175], v[72:79], 0, v143, v143 op_sel_hi:[0,0,0]
	v_mfma_scale_f32_16x16x128_f8f6f4 v[236:239], v[160:167], v[80:87], 0, v143, v143 op_sel_hi:[0,0,0]
	v_mfma_scale_f32_16x16x128_f8f6f4 v[240:243], v[168:175], v[80:87], 0, v143, v143 op_sel_hi:[0,0,0]
	v_mfma_scale_f32_16x16x128_f8f6f4 v[244:247], v[160:167], v[88:95], 0, v143, v143 op_sel_hi:[0,0,0]
	v_mfma_scale_f32_16x16x128_f8f6f4 v[248:251], v[168:175], v[88:95], 0, v143, v143 op_sel_hi:[0,0,0]
	s_setprio 0
	s_waitcnt vmcnt(8)
	s_barrier
	s_add_i32 s63, 0, 0x18000
	s_add_i32 s64, 0, 0x1c000
	s_nop 0
	v_add_u32_e32 v12, s63, v139
	v_add_u32_e32 v16, s64, v139
	ds_read_b128 v[0:3], v12
	ds_read_b128 v[4:7], v12 offset:1024
	ds_read_b128 v[8:11], v12 offset:2048
	ds_read_b128 v[12:15], v12 offset:3072
	ds_read_b128 v[144:147], v16
	ds_read_b128 v[148:151], v16 offset:1024
	ds_read_b128 v[152:155], v16 offset:2048
	ds_read_b128 v[156:159], v16 offset:3072
	s_add_u32 s54, s30, 0x40000
	v_mov_b32_e32 v64, v135
	v_mov_b32_e32 v65, v136
	s_addc_u32 s55, s31, 0
	s_mov_b32 m0, s42
	ds_read_b128 v[16:19], v142 offset:32768
	ds_read_b128 v[20:23], v142 offset:33792
	ds_read_b128 v[24:27], v142 offset:34816
	ds_read_b128 v[28:31], v142 offset:35840
	ds_read_b128 v[32:35], v142 offset:36864
	ds_read_b128 v[36:39], v142 offset:37888
	ds_read_b128 v[40:43], v142 offset:38912
	ds_read_b128 v[44:47], v142 offset:39936
	s_nop 0
	global_load_lds_dwordx4 v64, s[54:55]
	s_mov_b32 m0, s43
	s_nop 0
	global_load_lds_dwordx4 v65, s[54:55]
	s_and_b64 vcc, exec, s[14:15]
	s_cbranch_vccnz .Lmy_p4lw_23
	s_waitcnt vmcnt(8)

.Lmy_p4lw_24:
	s_waitcnt lgkmcnt(0)
	s_barrier
	s_setprio 1
	s_waitcnt lgkmcnt(0)
	v_mfma_scale_f32_16x16x128_f8f6f4 v[60:63], v[0:7], v[160:167], v[60:63], v143, v143 op_sel_hi:[0,0,0]
	v_mfma_scale_f32_16x16x128_f8f6f4 v[56:59], v[8:15], v[160:167], v[56:59], v143, v143 op_sel_hi:[0,0,0]
	v_mfma_scale_f32_16x16x128_f8f6f4 v[48:51], v[0:7], v[168:175], v[48:51], v143, v143 op_sel_hi:[0,0,0]
	v_mfma_scale_f32_16x16x128_f8f6f4 v[40:43], v[8:15], v[168:175], v[196:199], v143, v143 op_sel_hi:[0,0,0]
	v_mfma_scale_f32_16x16x128_f8f6f4 v[32:35], v[0:7], v[176:183], v[200:203], v143, v143 op_sel_hi:[0,0,0]
	v_mfma_scale_f32_16x16x128_f8f6f4 v[24:27], v[8:15], v[176:183], v[204:207], v143, v143 op_sel_hi:[0,0,0]
	v_mfma_scale_f32_16x16x128_f8f6f4 v[16:19], v[0:7], v[184:191], v[216:219], v143, v143 op_sel_hi:[0,0,0]
	v_mfma_scale_f32_16x16x128_f8f6f4 v[8:11], v[8:15], v[184:191], v[220:223], v143, v143 op_sel_hi:[0,0,0]
	s_setprio 0
	s_setprio 1
	v_mfma_scale_f32_16x16x128_f8f6f4 v[52:55], v[144:151], v[160:167], v[52:55], v143, v143 op_sel_hi:[0,0,0]
	v_mfma_scale_f32_16x16x128_f8f6f4 v[44:47], v[152:159], v[160:167], v[224:227], v143, v143 op_sel_hi:[0,0,0]
	v_mfma_scale_f32_16x16x128_f8f6f4 v[36:39], v[144:151], v[168:175], v[228:231], v143, v143 op_sel_hi:[0,0,0]
	v_mfma_scale_f32_16x16x128_f8f6f4 v[28:31], v[152:159], v[168:175], v[232:235], v143, v143 op_sel_hi:[0,0,0]
	v_mfma_scale_f32_16x16x128_f8f6f4 v[20:23], v[144:151], v[176:183], v[236:239], v143, v143 op_sel_hi:[0,0,0]
	v_mfma_scale_f32_16x16x128_f8f6f4 v[12:15], v[152:159], v[176:183], v[240:243], v143, v143 op_sel_hi:[0,0,0]
	v_mfma_scale_f32_16x16x128_f8f6f4 v[4:7], v[144:151], v[184:191], v[244:247], v143, v143 op_sel_hi:[0,0,0]
	v_mfma_scale_f32_16x16x128_f8f6f4 v[0:3], v[152:159], v[184:191], v[248:251], v143, v143 op_sel_hi:[0,0,0]
	s_setprio 0
	s_waitcnt vmcnt(8)
	s_barrier
	s_add_i32 s53, s53, 2
	s_add_u32 s19, s19, 0x80000
	s_addc_u32 s52, s52, 0
	s_add_u32 s28, s28, 0x100
	s_addc_u32 s29, s29, 0
	s_cmp_gt_u32 s53, 13
.LBB0_2964:
	ds_read_b128 v[144:147], v140
	ds_read_b128 v[148:151], v140 offset:1024
	ds_read_b128 v[152:155], v140 offset:2048
	ds_read_b128 v[156:159], v140 offset:3072
	ds_read_b128 v[160:163], v141
	ds_read_b128 v[164:167], v141 offset:1024
	ds_read_b128 v[168:171], v141 offset:2048
	ds_read_b128 v[172:175], v141 offset:3072
	s_add_u32 s30, s28, 0xfffc0080
	s_addc_u32 s31, s29, -1
	s_cmp_eq_u32 s53, 12
	s_cselect_b32 s31, s21, s31
	s_cselect_b32 s30, s20, s30
	s_cselect_b32 s35, s23, s52
	s_cselect_b32 s34, s22, s19
	v_mov_b32_e32 v128, v135
	v_mov_b32_e32 v130, v136
	s_add_i32 m0, s40, 0xc000
	ds_read_b128 v[176:179], v142
	ds_read_b128 v[180:183], v142 offset:1024
	ds_read_b128 v[184:187], v142 offset:2048
	ds_read_b128 v[188:191], v142 offset:3072
	ds_read_b128 v[192:195], v142 offset:4096
	ds_read_b128 v[196:199], v142 offset:5120
	ds_read_b128 v[200:203], v142 offset:6144
	ds_read_b128 v[204:207], v142 offset:7168
	s_nop 0
	global_load_lds_dwordx4 v128, s[28:29]
	s_add_i32 m0, s40, 0xe000
	s_nop 0
	global_load_lds_dwordx4 v130, s[28:29]
	s_and_b64 vcc, exec, s[14:15]
	s_cbranch_vccnz .Lmy_lw_21
	s_waitcnt vmcnt(8)
